# MLP-up epilogue: write-through (sc1) output stores keep the 16 MiB/XCD activation slab out of L2
# speedup vs baseline: 1.0396x; 1.0056x over previous
; __device__ __forceinline__ unsigned cvt_pk_bf16(float lo, float hi) { unsigned r; asm volatile("v_cvt_pk_bf16_f32 %0, %1, %2" : "=v"(r) : "v"(lo), "v"(hi)); return r; }
;     __device__ __forceinline__ void operator()(const f32x4 (&acc)[2][2][4][2], const Unit& u, int wr, int wc, int fr, int fq) const {
;     ...
;         for (int ai = 0; ai < 2; ++ai)
; #pragma unroll
;             for (int m = 0; m < 4; ++m) { const int row = row0 + ai * HALF + m * 16; bf16_t* rowp = base + (size_t)row * ldc + col0; float s1 = 0.f, s2 = 0.f;
;                 const float rs = rsv[ai][m];
; #pragma unroll
;                 for (int bj = 0; bj < 2; ++bj) { f32x4 v0 = acc[ai][bj][m][0] * rs, v1 = acc[ai][bj][m][1] * rs;
;                     if (ACT == 1) {
; #pragma unroll
;                         for (int e = 0; e < 4; ++e) { v0[e] = gelu_tanh(v0[e]); v1[e] = gelu_tanh(v1[e]); }
;                         s1 += ((v0[0] + v0[1]) + (v0[2] + v0[3])) + ((v1[0] + v1[1]) + (v1[2] + v1[3]));
;                         s2 += ((v0[0] * v0[0] + v0[1] * v0[1]) + (v0[2] * v0[2] + v0[3] * v0[3])) + ((v1[0] * v1[0] + v1[1] * v1[1]) + (v1[2] * v1[2] + v1[3] * v1[3]));
;                     }
;                     if (ACT == 2) {
; #pragma unroll
;                         for (int e = 0; e < 4; ++e) { const float a = __builtin_fmaxf(v0[e], 0.f), b = __builtin_fmaxf(v1[e], 0.f); v0[e] = a * a; v1[e] = b * b; }
;                     }
;                     u32x4 w; w.x = cvt_pk_bf16(v0[0], v0[1]); w.y = cvt_pk_bf16(v0[2], v0[3]); w.z = cvt_pk_bf16(v1[0], v1[1]); w.w = cvt_pk_bf16(v1[2], v1[3]);
;                     *(u32x4*)(rowp + bj * HALF) = w; }
.LBB0_863:
	v_pk_mul_f32 v[124:125], v[124:125], v[180:181] op_sel_hi:[1,0]
	v_lshl_or_b32 v134, s56, 8, v186
	v_pk_mul_f32 v[128:129], v[128:129], v[180:181] op_sel_hi:[1,0]
	v_pk_mul_f32 v[126:127], v[126:127], v[180:181] op_sel_hi:[1,0]
	v_max_f32_e32 v124, 0, v124
	v_ashrrev_i32_e32 v135, 31, v134
	v_pk_mul_f32 v[130:131], v[130:131], v[180:181] op_sel_hi:[1,0]
	v_mul_f32_e32 v133, v124, v124
	v_max_f32_e32 v124, 0, v129
	v_max_f32_e32 v125, 0, v125
	v_max_f32_e32 v126, 0, v126
	v_lshl_add_u64 v[134:135], v[134:135], 1, s[12:13]
	v_lshlrev_b64 v[138:139], 13, v[178:179]
	v_max_f32_e32 v128, 0, v128
	v_mul_f32_e32 v124, v124, v124
	v_mul_f32_e32 v129, v125, v125
	v_max_f32_e32 v125, 0, v130
	v_mul_f32_e32 v130, v126, v126
	v_max_f32_e32 v126, 0, v131
	v_max_f32_e32 v127, 0, v127
	v_pk_mul_f32 v[118:119], v[118:119], v[180:181] op_sel_hi:[1,0]
	v_pk_mul_f32 v[116:117], v[116:117], v[180:181] op_sel_hi:[1,0]
	v_lshl_add_u64 v[138:139], v[134:135], 0, v[138:139]
	v_mul_f32_e32 v128, v128, v128
	v_mul_f32_e32 v125, v125, v125
	v_mul_f32_e32 v126, v126, v126
	v_mul_f32_e32 v127, v127, v127
	v_cvt_pk_bf16_f32 v124, v128, v124
	v_pk_mul_f32 v[122:123], v[122:123], v[180:181] op_sel_hi:[1,0]
	v_pk_mul_f32 v[120:121], v[120:121], v[180:181] op_sel_hi:[1,0]
	v_max_f32_e32 v116, 0, v116
	v_max_f32_e32 v117, 0, v117
	v_max_f32_e32 v118, 0, v118
	v_cvt_pk_bf16_f32 v125, v125, v126
	v_cvt_pk_bf16_f32 v126, v133, v129
	v_cvt_pk_bf16_f32 v127, v130, v127
	global_store_dwordx4 v[138:139], v[124:127], off sc1
	v_max_f32_e32 v120, 0, v120
	v_max_f32_e32 v119, 0, v119
	v_mul_f32_e32 v124, v116, v116
	v_max_f32_e32 v116, 0, v121
	v_mul_f32_e32 v121, v117, v117
	v_max_f32_e32 v117, 0, v122
	v_mul_f32_e32 v122, v118, v118
	v_max_f32_e32 v118, 0, v123
	v_mul_f32_e32 v116, v116, v116
	v_mul_f32_e32 v117, v117, v117
	v_mul_f32_e32 v118, v118, v118
	v_pk_mul_f32 v[104:105], v[104:105], v[182:183] op_sel_hi:[1,0]
	v_mul_f32_e32 v120, v120, v120
	v_mul_f32_e32 v119, v119, v119
	v_cvt_pk_bf16_f32 v116, v120, v116
	v_cvt_pk_bf16_f32 v117, v117, v118
	v_cvt_pk_bf16_f32 v118, v124, v121
	v_pk_mul_f32 v[108:109], v[108:109], v[182:183] op_sel_hi:[1,0]
	v_pk_mul_f32 v[106:107], v[106:107], v[182:183] op_sel_hi:[1,0]
	v_max_f32_e32 v104, 0, v104
	v_cvt_pk_bf16_f32 v119, v122, v119
	global_store_dwordx4 v[138:139], v[116:119], off offset:256 sc1
	v_pk_mul_f32 v[110:111], v[110:111], v[182:183] op_sel_hi:[1,0]
	v_max_f32_e32 v105, 0, v105
	v_mul_f32_e32 v118, v104, v104
	v_max_f32_e32 v104, 0, v109
	v_max_f32_e32 v106, 0, v106
	v_lshlrev_b64 v[116:117], 13, v[176:177]
	v_max_f32_e32 v108, 0, v108
	v_mul_f32_e32 v104, v104, v104
	v_mul_f32_e32 v109, v105, v105
	v_max_f32_e32 v105, 0, v110
	v_mul_f32_e32 v110, v106, v106
	v_max_f32_e32 v106, 0, v111
	v_max_f32_e32 v107, 0, v107
	v_pk_mul_f32 v[98:99], v[98:99], v[182:183] op_sel_hi:[1,0]
	v_pk_mul_f32 v[96:97], v[96:97], v[182:183] op_sel_hi:[1,0]
	v_lshl_add_u64 v[116:117], v[134:135], 0, v[116:117]
	v_mul_f32_e32 v108, v108, v108
	v_mul_f32_e32 v105, v105, v105
	v_mul_f32_e32 v106, v106, v106
	v_mul_f32_e32 v107, v107, v107
	v_cvt_pk_bf16_f32 v104, v108, v104
	v_pk_mul_f32 v[102:103], v[102:103], v[182:183] op_sel_hi:[1,0]
	v_pk_mul_f32 v[100:101], v[100:101], v[182:183] op_sel_hi:[1,0]
	v_max_f32_e32 v96, 0, v96
	v_max_f32_e32 v97, 0, v97
	v_max_f32_e32 v98, 0, v98
	v_cvt_pk_bf16_f32 v105, v105, v106
	v_cvt_pk_bf16_f32 v106, v118, v109
	v_cvt_pk_bf16_f32 v107, v110, v107
	global_store_dwordx4 v[116:117], v[104:107], off sc1
	v_max_f32_e32 v100, 0, v100
	v_max_f32_e32 v99, 0, v99
	v_mul_f32_e32 v104, v96, v96
	v_max_f32_e32 v96, 0, v101
	v_mul_f32_e32 v101, v97, v97
	v_max_f32_e32 v97, 0, v102
	v_mul_f32_e32 v102, v98, v98
	v_max_f32_e32 v98, 0, v103
	v_mul_f32_e32 v96, v96, v96
	v_mul_f32_e32 v97, v97, v97
	v_mul_f32_e32 v98, v98, v98
	v_pk_mul_f32 v[88:89], v[88:89], v[152:153] op_sel_hi:[1,0]
	v_mul_f32_e32 v100, v100, v100
	v_mul_f32_e32 v99, v99, v99
	v_cvt_pk_bf16_f32 v96, v100, v96
	v_cvt_pk_bf16_f32 v97, v97, v98
	v_cvt_pk_bf16_f32 v98, v104, v101
	v_pk_mul_f32 v[92:93], v[92:93], v[152:153] op_sel_hi:[1,0]
	v_pk_mul_f32 v[90:91], v[90:91], v[152:153] op_sel_hi:[1,0]
	v_max_f32_e32 v88, 0, v88
	v_cvt_pk_bf16_f32 v99, v102, v99
	global_store_dwordx4 v[116:117], v[96:99], off offset:256 sc1
	v_pk_mul_f32 v[94:95], v[94:95], v[152:153] op_sel_hi:[1,0]
	v_max_f32_e32 v89, 0, v89
	v_mul_f32_e32 v98, v88, v88
	v_max_f32_e32 v88, 0, v93
	v_max_f32_e32 v90, 0, v90
	v_lshlrev_b64 v[96:97], 13, v[174:175]
	v_max_f32_e32 v92, 0, v92
	v_mul_f32_e32 v88, v88, v88
	v_mul_f32_e32 v93, v89, v89
	v_max_f32_e32 v89, 0, v94
	v_mul_f32_e32 v94, v90, v90
	v_max_f32_e32 v90, 0, v95
	v_max_f32_e32 v91, 0, v91
	v_pk_mul_f32 v[82:83], v[82:83], v[152:153] op_sel_hi:[1,0]
	v_pk_mul_f32 v[80:81], v[80:81], v[152:153] op_sel_hi:[1,0]
	v_lshl_add_u64 v[96:97], v[134:135], 0, v[96:97]
	v_mul_f32_e32 v92, v92, v92
	v_mul_f32_e32 v89, v89, v89
	v_mul_f32_e32 v90, v90, v90
	v_mul_f32_e32 v91, v91, v91
	v_cvt_pk_bf16_f32 v88, v92, v88
	v_pk_mul_f32 v[86:87], v[86:87], v[152:153] op_sel_hi:[1,0]
	v_pk_mul_f32 v[84:85], v[84:85], v[152:153] op_sel_hi:[1,0]
	v_max_f32_e32 v80, 0, v80
	v_max_f32_e32 v81, 0, v81
	v_max_f32_e32 v82, 0, v82
	v_cvt_pk_bf16_f32 v89, v89, v90
	v_cvt_pk_bf16_f32 v90, v98, v93
	v_cvt_pk_bf16_f32 v91, v94, v91
	global_store_dwordx4 v[96:97], v[88:91], off sc1
	v_max_f32_e32 v84, 0, v84
	v_max_f32_e32 v83, 0, v83
	v_mul_f32_e32 v88, v80, v80
	v_max_f32_e32 v80, 0, v85
	v_mul_f32_e32 v85, v81, v81
	v_max_f32_e32 v81, 0, v86
	v_mul_f32_e32 v86, v82, v82
	v_max_f32_e32 v82, 0, v87
	v_mul_f32_e32 v80, v80, v80
	v_mul_f32_e32 v81, v81, v81
; __device__ __forceinline__ unsigned cvt_pk_bf16(float lo, float hi) { unsigned r; asm volatile("v_cvt_pk_bf16_f32 %0, %1, %2" : "=v"(r) : "v"(lo), "v"(hi)); return r; }
;     __device__ __forceinline__ void operator()(const f32x4 (&acc)[2][2][4][2], const Unit& u, int wr, int wc, int fr, int fq) const {
;     ...
;         for (int ai = 0; ai < 2; ++ai)
; #pragma unroll
;             for (int m = 0; m < 4; ++m) { const int row = row0 + ai * HALF + m * 16; bf16_t* rowp = base + (size_t)row * ldc + col0; float s1 = 0.f, s2 = 0.f;
;                 const float rs = rsv[ai][m];
; #pragma unroll
;                 for (int bj = 0; bj < 2; ++bj) { f32x4 v0 = acc[ai][bj][m][0] * rs, v1 = acc[ai][bj][m][1] * rs;
;                     if (ACT == 1) {
; #pragma unroll
;                         for (int e = 0; e < 4; ++e) { v0[e] = gelu_tanh(v0[e]); v1[e] = gelu_tanh(v1[e]); }
;                         s1 += ((v0[0] + v0[1]) + (v0[2] + v0[3])) + ((v1[0] + v1[1]) + (v1[2] + v1[3]));
;                         s2 += ((v0[0] * v0[0] + v0[1] * v0[1]) + (v0[2] * v0[2] + v0[3] * v0[3])) + ((v1[0] * v1[0] + v1[1] * v1[1]) + (v1[2] * v1[2] + v1[3] * v1[3]));
;                     }
;                     if (ACT == 2) {
; #pragma unroll
;                         for (int e = 0; e < 4; ++e) { const float a = __builtin_fmaxf(v0[e], 0.f), b = __builtin_fmaxf(v1[e], 0.f); v0[e] = a * a; v1[e] = b * b; }
;                     }
;                     u32x4 w; w.x = cvt_pk_bf16(v0[0], v0[1]); w.y = cvt_pk_bf16(v0[2], v0[3]); w.z = cvt_pk_bf16(v1[0], v1[1]); w.w = cvt_pk_bf16(v1[2], v1[3]);
;                     *(u32x4*)(rowp + bj * HALF) = w; }
	v_mul_f32_e32 v82, v82, v82
	v_pk_mul_f32 v[72:73], v[72:73], v[148:149] op_sel_hi:[1,0]
	v_mul_f32_e32 v84, v84, v84
	v_mul_f32_e32 v83, v83, v83
	v_cvt_pk_bf16_f32 v80, v84, v80
	v_cvt_pk_bf16_f32 v81, v81, v82
	v_cvt_pk_bf16_f32 v82, v88, v85
	v_pk_mul_f32 v[76:77], v[76:77], v[148:149] op_sel_hi:[1,0]
	v_pk_mul_f32 v[74:75], v[74:75], v[148:149] op_sel_hi:[1,0]
	v_max_f32_e32 v72, 0, v72
	v_cvt_pk_bf16_f32 v83, v86, v83
	global_store_dwordx4 v[96:97], v[80:83], off offset:256 sc1
	v_pk_mul_f32 v[78:79], v[78:79], v[148:149] op_sel_hi:[1,0]
	v_max_f32_e32 v73, 0, v73
	v_mul_f32_e32 v82, v72, v72
	v_max_f32_e32 v72, 0, v77
	v_max_f32_e32 v74, 0, v74
	v_lshlrev_b64 v[80:81], 13, v[172:173]
	v_max_f32_e32 v76, 0, v76
	v_mul_f32_e32 v72, v72, v72
	v_mul_f32_e32 v77, v73, v73
	v_max_f32_e32 v73, 0, v78
	v_mul_f32_e32 v78, v74, v74
	v_max_f32_e32 v74, 0, v79
	v_max_f32_e32 v75, 0, v75
	v_pk_mul_f32 v[66:67], v[66:67], v[148:149] op_sel_hi:[1,0]
	v_pk_mul_f32 v[64:65], v[64:65], v[148:149] op_sel_hi:[1,0]
	v_lshl_add_u64 v[80:81], v[134:135], 0, v[80:81]
	v_mul_f32_e32 v76, v76, v76
	v_mul_f32_e32 v73, v73, v73
	v_mul_f32_e32 v74, v74, v74
	v_mul_f32_e32 v75, v75, v75
	v_cvt_pk_bf16_f32 v72, v76, v72
	v_pk_mul_f32 v[70:71], v[70:71], v[148:149] op_sel_hi:[1,0]
	v_pk_mul_f32 v[68:69], v[68:69], v[148:149] op_sel_hi:[1,0]
	v_max_f32_e32 v64, 0, v64
	v_max_f32_e32 v65, 0, v65
	v_max_f32_e32 v66, 0, v66
	v_cvt_pk_bf16_f32 v73, v73, v74
	v_cvt_pk_bf16_f32 v74, v82, v77
	v_cvt_pk_bf16_f32 v75, v78, v75
	global_store_dwordx4 v[80:81], v[72:75], off sc1
	v_max_f32_e32 v68, 0, v68
	v_max_f32_e32 v67, 0, v67
	v_mul_f32_e32 v72, v64, v64
	v_max_f32_e32 v64, 0, v69
	v_mul_f32_e32 v69, v65, v65
	v_max_f32_e32 v65, 0, v70
	v_mul_f32_e32 v70, v66, v66
	v_max_f32_e32 v66, 0, v71
	v_mul_f32_e32 v64, v64, v64
	v_mul_f32_e32 v65, v65, v65
	v_mul_f32_e32 v66, v66, v66
	v_pk_mul_f32 v[56:57], v[56:57], v[144:145] op_sel_hi:[1,0]
	v_mul_f32_e32 v68, v68, v68
	v_mul_f32_e32 v67, v67, v67
	v_cvt_pk_bf16_f32 v64, v68, v64
	v_cvt_pk_bf16_f32 v65, v65, v66
	v_cvt_pk_bf16_f32 v66, v72, v69
	v_pk_mul_f32 v[60:61], v[60:61], v[144:145] op_sel_hi:[1,0]
	v_pk_mul_f32 v[58:59], v[58:59], v[144:145] op_sel_hi:[1,0]
	v_max_f32_e32 v56, 0, v56
	v_cvt_pk_bf16_f32 v67, v70, v67
	global_store_dwordx4 v[80:81], v[64:67], off offset:256 sc1
	v_pk_mul_f32 v[62:63], v[62:63], v[144:145] op_sel_hi:[1,0]
	v_max_f32_e32 v57, 0, v57
	v_mul_f32_e32 v66, v56, v56
	v_max_f32_e32 v56, 0, v61
	v_max_f32_e32 v58, 0, v58
	v_lshlrev_b64 v[64:65], 13, v[170:171]
	v_max_f32_e32 v60, 0, v60
	v_mul_f32_e32 v56, v56, v56
	v_mul_f32_e32 v61, v57, v57
	v_max_f32_e32 v57, 0, v62
	v_mul_f32_e32 v62, v58, v58
	v_max_f32_e32 v58, 0, v63
	v_max_f32_e32 v59, 0, v59
	v_pk_mul_f32 v[50:51], v[50:51], v[144:145] op_sel_hi:[1,0]
	v_pk_mul_f32 v[48:49], v[48:49], v[144:145] op_sel_hi:[1,0]
	v_lshl_add_u64 v[64:65], v[134:135], 0, v[64:65]
	v_mul_f32_e32 v60, v60, v60
	v_mul_f32_e32 v57, v57, v57
	v_mul_f32_e32 v58, v58, v58
	v_mul_f32_e32 v59, v59, v59
	v_cvt_pk_bf16_f32 v56, v60, v56
	v_pk_mul_f32 v[54:55], v[54:55], v[144:145] op_sel_hi:[1,0]
	v_pk_mul_f32 v[52:53], v[52:53], v[144:145] op_sel_hi:[1,0]
	v_max_f32_e32 v48, 0, v48
	v_max_f32_e32 v49, 0, v49
	v_max_f32_e32 v50, 0, v50
	v_cvt_pk_bf16_f32 v57, v57, v58
	v_cvt_pk_bf16_f32 v58, v66, v61
	v_cvt_pk_bf16_f32 v59, v62, v59
	global_store_dwordx4 v[64:65], v[56:59], off sc1
	v_max_f32_e32 v52, 0, v52
	v_max_f32_e32 v51, 0, v51
	v_mul_f32_e32 v56, v48, v48
	v_max_f32_e32 v48, 0, v53
	v_mul_f32_e32 v53, v49, v49
	v_max_f32_e32 v49, 0, v54
	v_mul_f32_e32 v54, v50, v50
	v_max_f32_e32 v50, 0, v55
	v_mul_f32_e32 v48, v48, v48
	v_mul_f32_e32 v49, v49, v49
	v_mul_f32_e32 v50, v50, v50
	v_pk_mul_f32 v[40:41], v[40:41], v[140:141] op_sel_hi:[1,0]
	v_mul_f32_e32 v52, v52, v52
	v_mul_f32_e32 v51, v51, v51
	v_cvt_pk_bf16_f32 v48, v52, v48
	v_cvt_pk_bf16_f32 v49, v49, v50
	v_cvt_pk_bf16_f32 v50, v56, v53
	v_pk_mul_f32 v[44:45], v[44:45], v[140:141] op_sel_hi:[1,0]
	v_pk_mul_f32 v[42:43], v[42:43], v[140:141] op_sel_hi:[1,0]
	v_max_f32_e32 v40, 0, v40
	v_cvt_pk_bf16_f32 v51, v54, v51
	global_store_dwordx4 v[64:65], v[48:51], off offset:256 sc1
	v_pk_mul_f32 v[46:47], v[46:47], v[140:141] op_sel_hi:[1,0]
	v_max_f32_e32 v41, 0, v41
	v_mul_f32_e32 v50, v40, v40
	v_max_f32_e32 v40, 0, v45
	v_max_f32_e32 v42, 0, v42
	v_lshlrev_b64 v[48:49], 13, v[168:169]
	v_max_f32_e32 v44, 0, v44
	v_mul_f32_e32 v40, v40, v40
	v_mul_f32_e32 v45, v41, v41
	v_max_f32_e32 v41, 0, v46
	v_mul_f32_e32 v46, v42, v42
	v_max_f32_e32 v42, 0, v47
	v_max_f32_e32 v43, 0, v43
	v_pk_mul_f32 v[34:35], v[34:35], v[140:141] op_sel_hi:[1,0]
	v_pk_mul_f32 v[32:33], v[32:33], v[140:141] op_sel_hi:[1,0]
	v_lshl_add_u64 v[48:49], v[134:135], 0, v[48:49]
	v_mul_f32_e32 v44, v44, v44
; __device__ __forceinline__ unsigned cvt_pk_bf16(float lo, float hi) { unsigned r; asm volatile("v_cvt_pk_bf16_f32 %0, %1, %2" : "=v"(r) : "v"(lo), "v"(hi)); return r; }
;     __device__ __forceinline__ void operator()(const f32x4 (&acc)[2][2][4][2], const Unit& u, int wr, int wc, int fr, int fq) const {
;     ...
;         for (int ai = 0; ai < 2; ++ai)
; #pragma unroll
;             for (int m = 0; m < 4; ++m) { const int row = row0 + ai * HALF + m * 16; bf16_t* rowp = base + (size_t)row * ldc + col0; float s1 = 0.f, s2 = 0.f;
;                 const float rs = rsv[ai][m];
; #pragma unroll
;                 for (int bj = 0; bj < 2; ++bj) { f32x4 v0 = acc[ai][bj][m][0] * rs, v1 = acc[ai][bj][m][1] * rs;
;                     if (ACT == 1) {
; #pragma unroll
;                         for (int e = 0; e < 4; ++e) { v0[e] = gelu_tanh(v0[e]); v1[e] = gelu_tanh(v1[e]); }
;                         s1 += ((v0[0] + v0[1]) + (v0[2] + v0[3])) + ((v1[0] + v1[1]) + (v1[2] + v1[3]));
;                         s2 += ((v0[0] * v0[0] + v0[1] * v0[1]) + (v0[2] * v0[2] + v0[3] * v0[3])) + ((v1[0] * v1[0] + v1[1] * v1[1]) + (v1[2] * v1[2] + v1[3] * v1[3]));
;                     }
;                     if (ACT == 2) {
; #pragma unroll
;                         for (int e = 0; e < 4; ++e) { const float a = __builtin_fmaxf(v0[e], 0.f), b = __builtin_fmaxf(v1[e], 0.f); v0[e] = a * a; v1[e] = b * b; }
;                     }
;                     u32x4 w; w.x = cvt_pk_bf16(v0[0], v0[1]); w.y = cvt_pk_bf16(v0[2], v0[3]); w.z = cvt_pk_bf16(v1[0], v1[1]); w.w = cvt_pk_bf16(v1[2], v1[3]);
;                     *(u32x4*)(rowp + bj * HALF) = w; }
	v_mul_f32_e32 v41, v41, v41
	v_mul_f32_e32 v42, v42, v42
	v_mul_f32_e32 v43, v43, v43
	v_cvt_pk_bf16_f32 v40, v44, v40
	v_pk_mul_f32 v[38:39], v[38:39], v[140:141] op_sel_hi:[1,0]
	v_pk_mul_f32 v[36:37], v[36:37], v[140:141] op_sel_hi:[1,0]
	v_max_f32_e32 v32, 0, v32
	v_max_f32_e32 v33, 0, v33
	v_max_f32_e32 v34, 0, v34
	v_cvt_pk_bf16_f32 v41, v41, v42
	v_cvt_pk_bf16_f32 v42, v50, v45
	v_cvt_pk_bf16_f32 v43, v46, v43
	global_store_dwordx4 v[48:49], v[40:43], off sc1
	v_max_f32_e32 v36, 0, v36
	v_max_f32_e32 v35, 0, v35
	v_mul_f32_e32 v40, v32, v32
	v_max_f32_e32 v32, 0, v37
	v_mul_f32_e32 v37, v33, v33
	v_max_f32_e32 v33, 0, v38
	v_mul_f32_e32 v38, v34, v34
	v_max_f32_e32 v34, 0, v39
	v_mul_f32_e32 v32, v32, v32
	v_mul_f32_e32 v33, v33, v33
	v_mul_f32_e32 v34, v34, v34
	v_pk_mul_f32 v[24:25], v[24:25], v[136:137] op_sel_hi:[1,0]
	v_mul_f32_e32 v36, v36, v36
	v_mul_f32_e32 v35, v35, v35
	v_cvt_pk_bf16_f32 v32, v36, v32
	v_cvt_pk_bf16_f32 v33, v33, v34
	v_cvt_pk_bf16_f32 v34, v40, v37
	v_pk_mul_f32 v[28:29], v[28:29], v[136:137] op_sel_hi:[1,0]
	v_pk_mul_f32 v[26:27], v[26:27], v[136:137] op_sel_hi:[1,0]
	v_max_f32_e32 v24, 0, v24
	v_cvt_pk_bf16_f32 v35, v38, v35
	global_store_dwordx4 v[48:49], v[32:35], off offset:256 sc1
	v_pk_mul_f32 v[30:31], v[30:31], v[136:137] op_sel_hi:[1,0]
	v_max_f32_e32 v25, 0, v25
	v_mul_f32_e32 v34, v24, v24
	v_max_f32_e32 v24, 0, v29
	v_max_f32_e32 v26, 0, v26
	v_lshlrev_b64 v[32:33], 13, v[166:167]
	v_max_f32_e32 v28, 0, v28
	v_mul_f32_e32 v24, v24, v24
	v_mul_f32_e32 v29, v25, v25
	v_max_f32_e32 v25, 0, v30
	v_mul_f32_e32 v30, v26, v26
	v_max_f32_e32 v26, 0, v31
	v_max_f32_e32 v27, 0, v27
	v_pk_mul_f32 v[18:19], v[18:19], v[136:137] op_sel_hi:[1,0]
	v_pk_mul_f32 v[16:17], v[16:17], v[136:137] op_sel_hi:[1,0]
	v_lshl_add_u64 v[32:33], v[134:135], 0, v[32:33]
	v_mul_f32_e32 v28, v28, v28
	v_mul_f32_e32 v25, v25, v25
	v_mul_f32_e32 v26, v26, v26
	v_mul_f32_e32 v27, v27, v27
	v_cvt_pk_bf16_f32 v24, v28, v24
	v_pk_mul_f32 v[22:23], v[22:23], v[136:137] op_sel_hi:[1,0]
	v_pk_mul_f32 v[20:21], v[20:21], v[136:137] op_sel_hi:[1,0]
	v_max_f32_e32 v16, 0, v16
	v_max_f32_e32 v17, 0, v17
	v_max_f32_e32 v18, 0, v18
	v_cvt_pk_bf16_f32 v25, v25, v26
	v_cvt_pk_bf16_f32 v26, v34, v29
	v_cvt_pk_bf16_f32 v27, v30, v27
	global_store_dwordx4 v[32:33], v[24:27], off sc1
	v_max_f32_e32 v20, 0, v20
	v_max_f32_e32 v19, 0, v19
	v_mul_f32_e32 v24, v16, v16
	v_max_f32_e32 v16, 0, v21
	v_mul_f32_e32 v21, v17, v17
	v_max_f32_e32 v17, 0, v22
	v_mul_f32_e32 v22, v18, v18
	v_max_f32_e32 v18, 0, v23
	v_mul_f32_e32 v16, v16, v16
	v_mul_f32_e32 v17, v17, v17
	v_mul_f32_e32 v18, v18, v18
	v_pk_mul_f32 v[8:9], v[8:9], v[132:133] op_sel_hi:[1,0]
	v_mul_f32_e32 v20, v20, v20
	v_mul_f32_e32 v19, v19, v19
	v_cvt_pk_bf16_f32 v16, v20, v16
	v_cvt_pk_bf16_f32 v17, v17, v18
	v_cvt_pk_bf16_f32 v18, v24, v21
	v_pk_mul_f32 v[12:13], v[12:13], v[132:133] op_sel_hi:[1,0]
	v_pk_mul_f32 v[10:11], v[10:11], v[132:133] op_sel_hi:[1,0]
	v_max_f32_e32 v8, 0, v8
	v_cvt_pk_bf16_f32 v19, v22, v19
	global_store_dwordx4 v[32:33], v[16:19], off offset:256 sc1
	v_pk_mul_f32 v[14:15], v[14:15], v[132:133] op_sel_hi:[1,0]
	v_max_f32_e32 v9, 0, v9
	v_mul_f32_e32 v18, v8, v8
	v_max_f32_e32 v8, 0, v13
	v_max_f32_e32 v10, 0, v10
	v_lshlrev_b64 v[16:17], 13, v[164:165]
	v_max_f32_e32 v12, 0, v12
	v_mul_f32_e32 v8, v8, v8
	v_mul_f32_e32 v13, v9, v9
	v_max_f32_e32 v9, 0, v14
	v_mul_f32_e32 v14, v10, v10
	v_max_f32_e32 v10, 0, v15
	v_max_f32_e32 v11, 0, v11
	v_pk_mul_f32 v[2:3], v[2:3], v[132:133] op_sel_hi:[1,0]
	v_pk_mul_f32 v[0:1], v[0:1], v[132:133] op_sel_hi:[1,0]
	v_lshl_add_u64 v[16:17], v[134:135], 0, v[16:17]
	v_mul_f32_e32 v12, v12, v12
	v_mul_f32_e32 v9, v9, v9
	v_mul_f32_e32 v10, v10, v10
	v_mul_f32_e32 v11, v11, v11
	v_cvt_pk_bf16_f32 v8, v12, v8
	v_pk_mul_f32 v[6:7], v[6:7], v[132:133] op_sel_hi:[1,0]
	v_pk_mul_f32 v[4:5], v[4:5], v[132:133] op_sel_hi:[1,0]
	v_max_f32_e32 v0, 0, v0
	v_max_f32_e32 v1, 0, v1
	v_max_f32_e32 v2, 0, v2
	v_cvt_pk_bf16_f32 v9, v9, v10
	v_cvt_pk_bf16_f32 v10, v18, v13
	v_cvt_pk_bf16_f32 v11, v14, v11
	global_store_dwordx4 v[16:17], v[8:11], off sc1
	v_max_f32_e32 v3, 0, v3
	v_max_f32_e32 v4, 0, v4
	v_mul_f32_e32 v8, v0, v0
	v_max_f32_e32 v0, 0, v5
	v_mul_f32_e32 v5, v1, v1
	v_max_f32_e32 v1, 0, v6
	v_mul_f32_e32 v6, v2, v2
	v_max_f32_e32 v2, 0, v7
	v_mul_f32_e32 v0, v0, v0
	v_mul_f32_e32 v1, v1, v1
	v_mul_f32_e32 v2, v2, v2
	v_mul_f32_e32 v3, v3, v3
	s_andn2_b64 vcc, exec, s[4:5]
	s_mov_b64 s[4:5], -1
	v_mul_f32_e32 v4, v4, v4
	v_cvt_pk_bf16_f32 v0, v4, v0
	v_cvt_pk_bf16_f32 v1, v1, v2
	v_cvt_pk_bf16_f32 v2, v8, v5
	v_cvt_pk_bf16_f32 v3, v6, v3
	global_store_dwordx4 v[16:17], v[0:3], off offset:256 sc1
	s_cbranch_vccnz .LBB0_848
	s_andn2_b64 vcc, exec, s[8:9]
	s_cbranch_vccnz .LBB0_847
	s_barrier
	s_branch .LBB0_847
